# k28 + attention key loops: first key tile's K fragments for the next step prefetched at the start of the PV block (software pipelining across the key loop)
# baseline (speedup 1.0000x reference)
; #define LAS __attribute__((address_space(3)))
; __device__ __forceinline__ v4i16_t vtr(const LAS unsigned char* p) { return __builtin_amdgcn_ds_read_tr16_b64_v4i16((LAS v4i16_t*)p); }
; #define MFMA16(a, b, c) __builtin_amdgcn_mfma_f32_16x16x32_bf16((a), (b), (c), 0, 0, 0)
; template <int PASS>
; __device__ __forceinline__ void attn_pass(const Frame& F, const bf16_t* QKVA, bf16_t* OACC, float* LACC, bf16_t* Hout, float nb2) {
;     ...
;         f32x4 accO[8];
;         bf16_t* op = OACC + tq * 1024 + h * 128 + 4 * g;
;         float lsum = 0.f;
;         if (PASS > 0) {
; #pragma unroll
;             for (int nt = 0; nt < 8; ++nt) { const u32x2 pv = *(const u32x2*)(op + 16 * nt); accO[nt] = (f32x4){bflo(pv.x), bfhi(pv.x), bflo(pv.y), bfhi(pv.y)}; }
;             lsum = (g == 0) ? LACC[tq * 8 + h] : 0.f;
;         } else {
; #pragma unroll
;             for (int nt = 0; nt < 8; ++nt) accO[nt] = (f32x4){0.f, 0.f, 0.f, 0.f};
;         }
; #pragma unroll 1
;         for (int ks = 0; ks < 5; ++ks) {
;     ...
;             const bf16x8 pa = __builtin_bit_cast(bf16x8, pw);
;             const int kt0 = w + 2 * ks, kt1 = (kt0 + 1 < 16) ? kt0 + 1 : 15;
;             const LAS unsigned char* v0 = Vl + (16 * kt0 + 4 * g + q4) * VST + 8 * p4;
;             const LAS unsigned char* v1 = Vl + (16 * kt1 + 4 * g + q4) * VST + 8 * p4;
; #pragma unroll
;             for (int nt = 0; nt < 8; ++nt) {
;                 const v4i16_t lo = vtr(v0 + 32 * nt), hi = vtr(v1 + 32 * nt);
;                 const bf16x8 vf = __builtin_shufflevector(lo, hi, 0, 1, 2, 3, 4, 5, 6, 7);
;                 accO[nt] = MFMA16(vf, pa, accO[nt]);
;             }
.LBB0_478:
	s_ashr_i32 s20, s41, 3
	v_mov_b32_e32 v179, 0
	s_cmp_gt_i32 s20, 0
	s_mov_b32 s42, 0
	s_cselect_b64 s[24:25], -1, 0
	v_mov_b32_e32 v178, v165
	s_mov_b32 s43, s65
	v_mov_b32_e32 v96, 0
	v_mov_b32_e32 v97, v179
	v_mov_b32_e32 v98, v179
	v_mov_b32_e32 v99, v179
	v_mov_b32_e32 v100, 0
	v_mov_b32_e32 v101, v179
	v_mov_b32_e32 v102, v179
	v_mov_b32_e32 v103, v179
	v_mov_b32_e32 v104, 0
	v_mov_b32_e32 v105, v179
	v_mov_b32_e32 v106, v179
	v_mov_b32_e32 v107, v179
	v_mov_b32_e32 v108, 0
	v_mov_b32_e32 v109, v179
	v_mov_b32_e32 v110, v179
	v_mov_b32_e32 v111, v179
	v_mov_b32_e32 v112, 0
	v_mov_b32_e32 v113, v179
	v_mov_b32_e32 v114, v179
	v_mov_b32_e32 v115, v179
	v_mov_b32_e32 v116, 0
	v_mov_b32_e32 v117, v179
	v_mov_b32_e32 v118, v179
	v_mov_b32_e32 v119, v179
	v_mov_b32_e32 v120, 0
	v_mov_b32_e32 v121, v179
	v_mov_b32_e32 v122, v179
	v_mov_b32_e32 v123, v179
	v_mov_b32_e32 v124, 0
	v_mov_b32_e32 v125, v179
	v_mov_b32_e32 v126, v179
	v_mov_b32_e32 v127, v179
	s_min_i32 s98, s43, 15
	v_lshl_or_b32 v250, s98, 4, v135
	v_mad_u64_u32 v[252:253], s[98:99], v250, s28, v[150:151]
	ds_read_b128 v[214:217], v252
	ds_read_b128 v[218:221], v252 offset:64
	ds_read_b128 v[222:225], v252 offset:128
	ds_read_b128 v[226:229], v252 offset:192
	s_branch .LBB0_480
.LBB0_479:
	s_add_i32 s4, s43, 2
	s_min_i32 s4, s4, 15
	v_lshl_or_b32 v250, s4, 4, v135
	v_mad_u64_u32 v[252:253], s[4:5], v250, s28, v[150:151]
	ds_read_b128 v[214:217], v252
	ds_read_b128 v[218:221], v252 offset:64
	ds_read_b128 v[222:225], v252 offset:128
	ds_read_b128 v[226:229], v252 offset:192
	s_min_i32 s4, s43, 14
	v_add_u32_e32 v182, 0xffffff20, v178
	v_lshl_add_u32 v183, s4, 4, v160
	v_mad_u64_u32 v[198:199], s[4:5], v183, s29, v[152:153]
	ds_read_b64_tr_b16 v[182:183], v182
	ds_read_b64_tr_b16 v[184:185], v198
	v_cvt_pk_bf16_f32 v128, v128, v129
	v_cvt_pk_bf16_f32 v129, v180, v181
	v_add_u32_e32 v180, 0xffffff40, v178
	ds_read_b64_tr_b16 v[186:187], v180
	ds_read_b64_tr_b16 v[188:189], v198 offset:32
	ds_read_b64_tr_b16 v[192:193], v198 offset:64
	ds_read_b64_tr_b16 v[196:197], v198 offset:96
	v_add_u32_e32 v180, 0xffffff60, v178
	ds_read_b64_tr_b16 v[190:191], v180
	v_add_u32_e32 v180, 0xffffff80, v178
	v_add_u32_e32 v181, 0xffffffa0, v178
	s_waitcnt lgkmcnt(5)
	v_mfma_f32_16x16x32_bf16 v[124:127], v[182:185], v[128:131], v[124:127]
	ds_read_b64_tr_b16 v[194:195], v180
	ds_read_b64_tr_b16 v[180:181], v181
	ds_read_b64_tr_b16 v[182:183], v198 offset:128
	v_subrev_u32_e32 v184, 64, v178
	s_waitcnt lgkmcnt(0)
	v_mfma_f32_16x16x32_bf16 v[108:111], v[180:183], v[128:131], v[108:111]
	v_subrev_u32_e32 v180, 32, v178
	s_add_i32 s42, s42, 32
	s_add_i32 s43, s43, 2
	v_mfma_f32_16x16x32_bf16 v[120:123], v[186:189], v[128:131], v[120:123]
	s_cmpk_eq_i32 s42, 0xa0
	v_mfma_f32_16x16x32_bf16 v[116:119], v[190:193], v[128:131], v[116:119]
	v_mfma_f32_16x16x32_bf16 v[112:115], v[194:197], v[128:131], v[112:115]
	ds_read_b64_tr_b16 v[184:185], v184
	ds_read_b64_tr_b16 v[186:187], v198 offset:160
	ds_read_b64_tr_b16 v[190:191], v198 offset:192
	ds_read_b64_tr_b16 v[194:195], v198 offset:224
	ds_read_b64_tr_b16 v[188:189], v180
	ds_read_b64_tr_b16 v[192:193], v178
	v_add_u32_e32 v178, 0x2400, v178
	s_waitcnt lgkmcnt(4)
	v_mfma_f32_16x16x32_bf16 v[104:107], v[184:187], v[128:131], v[104:107]
	s_waitcnt lgkmcnt(1)
	v_mfma_f32_16x16x32_bf16 v[100:103], v[188:191], v[128:131], v[100:103]
	s_waitcnt lgkmcnt(0)
	v_mfma_f32_16x16x32_bf16 v[96:99], v[192:195], v[128:131], v[96:99]
	s_cbranch_scc1 .LBB0_484
; #define LAS __attribute__((address_space(3)))
; __device__ __forceinline__ unsigned cvtpk_s(float lo, float hi) { f32x2_t v = {lo, hi}; bf16x2_t b = __builtin_convertvector(v, bf16x2_t); return __builtin_bit_cast(unsigned, b); }
; #define MFMA16(a, b, c) __builtin_amdgcn_mfma_f32_16x16x32_bf16((a), (b), (c), 0, 0, 0)
; template <int PASS>
; __device__ __forceinline__ void attn_pass(const Frame& F, const bf16_t* QKVA, bf16_t* OACC, float* LACC, bf16_t* Hout, float nb2) {
;     ...
;         for (int ks = 0; ks < 5; ++ks) {
;             u32x4 pw;
; #pragma unroll
;             for (int half = 0; half < 2; ++half) {
;                 const int kt = w + 2 * ks + half; const int ktc = kt < 16 ? kt : 15;
;                 if (ks == 4 && half == 1) { pw.z = 0u; pw.w = 0u; continue; }
;                 f32x4 sv = (f32x4){0.f, 0.f, 0.f, 0.f};
; #pragma unroll
;                 for (int kk = 0; kk < 4; ++kk) { const bf16x8 a = *(const LAS bf16x8*)(Kl + (16 * ktc + c) * KST + (8 * g + 32 * kk) * 2); sv = MFMA16(a, qf[kk], sv); }
;                 float pj[4];
; #pragma unroll
;                 for (int j = 0; j < 4; ++j) { const int kj = 16 * kt + 4 * g + j; const bool valid = (kj >= qi) && (kj <= qi + 128) && (n > 0 || kj >= 128);
;                     pj[j] = valid ? __builtin_amdgcn_exp2f(sv[j] * SCL + nb2) : 0.f; lsum += pj[j]; }
;                 if (half == 0) { pw.x = cvtpk_s(pj[0], pj[1]); pw.y = cvtpk_s(pj[2], pj[3]); } else { pw.z = cvtpk_s(pj[0], pj[1]); pw.w = cvtpk_s(pj[2], pj[3]); }
;             }
.LBB0_480:
	s_add_i32 s4, s43, 1
	s_min_i32 s4, s4, 15
	v_lshl_or_b32 v246, s4, 4, v135
	v_mad_u64_u32 v[248:249], s[4:5], v246, s28, v[150:151]
	ds_read_b128 v[230:233], v248
	ds_read_b128 v[234:237], v248 offset:64
	ds_read_b128 v[238:241], v248 offset:128
	ds_read_b128 v[242:245], v248 offset:192
	s_waitcnt lgkmcnt(7)
	v_mfma_f32_16x16x32_bf16 v[180:183], v[214:217], v[28:31], 0
	v_add_u32_e32 v130, s42, v164
	v_add_u32_e32 v128, 1, v130
	v_cmp_lt_i32_e64 s[12:13], v128, v158
	s_waitcnt lgkmcnt(6)
	v_mfma_f32_16x16x32_bf16 v[180:183], v[218:221], v[24:27], v[180:183]
	v_cmp_lt_i32_e32 vcc, v130, v158
	v_cmp_gt_i32_e64 s[4:5], v130, v159
	v_cmp_lt_i32_e64 s[6:7], s38, v130
	s_waitcnt lgkmcnt(5)
	v_mfma_f32_16x16x32_bf16 v[180:183], v[222:225], v[20:23], v[180:183]
	v_cmp_lt_i32_e64 s[10:11], s39, v130
	v_add_u32_e32 v129, 2, v130
	s_or_b64 s[6:7], s[24:25], s[6:7]
	s_waitcnt lgkmcnt(4)
	v_mfma_f32_16x16x32_bf16 v[180:183], v[226:229], v[16:19], v[180:183]
	s_or_b64 s[34:35], vcc, s[4:5]
	s_or_b64 vcc, s[24:25], s[10:11]
	v_cmp_ge_i32_e64 s[8:9], v130, v159
	v_cmp_lt_i32_e64 s[14:15], v129, v158
	v_cmp_lt_i32_e64 s[4:5], s38, v129
	s_nop 2
	v_fmamk_f32 v128, v180, 0x3e0293ee, v208
	v_fmamk_f32 v131, v181, 0x3e0293ee, v208
	v_exp_f32_e32 v128, v128
	v_exp_f32_e32 v131, v131
	v_fmamk_f32 v180, v182, 0x3e0293ee, v208
	v_exp_f32_e32 v180, v180
	v_fmamk_f32 v181, v183, 0x3e0293ee, v208
	v_exp_f32_e32 v181, v181
	v_cndmask_b32_e64 v128, 0, v128, s[6:7]
	v_cndmask_b32_e32 v131, 0, v131, vcc
	v_cmp_gt_i32_e32 vcc, v129, v159
	v_add_u32_e32 v129, 3, v130
	s_or_b64 s[8:9], s[12:13], s[8:9]
	s_or_b64 s[4:5], s[24:25], s[4:5]
	v_cmp_lt_i32_e64 s[6:7], s38, v129
	v_cndmask_b32_e64 v128, v128, 0, s[34:35]
	v_cndmask_b32_e64 v180, 0, v180, s[4:5]
	s_or_b64 s[10:11], s[14:15], vcc
	v_cmp_lt_i32_e32 vcc, v129, v158
	v_cmp_gt_i32_e64 s[4:5], v129, v159
	s_or_b64 s[6:7], s[24:25], s[6:7]
	v_add_f32_e32 v179, v179, v128
	v_cndmask_b32_e64 v129, v131, 0, s[8:9]
	v_cndmask_b32_e64 v181, 0, v181, s[6:7]
	s_or_b64 s[4:5], vcc, s[4:5]
	v_add_f32_e32 v131, v129, v179
	v_cndmask_b32_e64 v180, v180, 0, s[10:11]
	v_add_f32_e32 v131, v180, v131
	v_cndmask_b32_e64 v181, v181, 0, s[4:5]
	s_cmpk_lg_i32 s42, 0x80
	v_add_f32_e32 v182, v181, v131
	s_mov_b64 s[4:5], -1
	s_cbranch_scc0 .LBB0_482
	s_waitcnt lgkmcnt(3)
	v_mfma_f32_16x16x32_bf16 v[184:187], v[230:233], v[28:31], 0
	v_add_u32_e32 v131, 16, v130
	v_add_u32_e32 v179, 17, v130
	v_cmp_lt_i32_e32 vcc, v131, v158
	s_waitcnt lgkmcnt(2)
	v_mfma_f32_16x16x32_bf16 v[184:187], v[234:237], v[24:27], v[184:187]
	v_cmp_gt_i32_e64 s[4:5], v131, v159
	v_cmp_lt_i32_e64 s[6:7], s38, v131
	v_cmp_ge_i32_e64 s[10:11], v131, v159
	s_waitcnt lgkmcnt(1)
	v_mfma_f32_16x16x32_bf16 v[184:187], v[238:241], v[20:23], v[184:187]
	v_cmp_lt_i32_e64 s[12:13], s39, v131
	v_cmp_lt_i32_e64 s[8:9], v179, v158
	s_or_b64 s[6:7], s[24:25], s[6:7]
	s_waitcnt lgkmcnt(0)
	v_mfma_f32_16x16x32_bf16 v[184:187], v[242:245], v[16:19], v[184:187]
	s_or_b64 s[4:5], vcc, s[4:5]
	v_add_u32_e32 v183, 18, v130
	v_cmp_lt_i32_e64 s[14:15], v183, v158
	v_cmp_gt_i32_e32 vcc, v183, v159
	v_add_u32_e32 v130, 19, v130
	s_nop 2
	v_fmamk_f32 v131, v184, 0x3e0293ee, v208
	v_fmamk_f32 v179, v185, 0x3e0293ee, v208
	v_exp_f32_e32 v131, v131
	v_exp_f32_e32 v179, v179
	v_fmamk_f32 v184, v186, 0x3e0293ee, v208
	v_exp_f32_e32 v184, v184
	v_cndmask_b32_e64 v131, 0, v131, s[6:7]
	s_or_b64 s[6:7], s[24:25], s[12:13]
	v_cndmask_b32_e64 v179, 0, v179, s[6:7]
	v_cndmask_b32_e64 v131, v131, 0, s[4:5]
	s_or_b64 s[4:5], s[8:9], s[10:11]
	v_cndmask_b32_e64 v185, v179, 0, s[4:5]
	v_cmp_lt_i32_e64 s[4:5], s38, v183
	s_or_b64 s[4:5], s[24:25], s[4:5]
	v_cmp_lt_i32_e64 s[6:7], s38, v130
	v_cndmask_b32_e64 v183, 0, v184, s[4:5]
	v_fmamk_f32 v184, v187, 0x3e0293ee, v208
	v_exp_f32_e32 v184, v184
	s_or_b64 s[4:5], s[14:15], vcc
	v_add_f32_e32 v179, v182, v131
	v_cndmask_b32_e64 v183, v183, 0, s[4:5]
	v_cmp_lt_i32_e32 vcc, v130, v158
	v_cmp_gt_i32_e64 s[4:5], v130, v159
	s_or_b64 s[6:7], s[24:25], s[6:7]
	v_add_f32_e32 v179, v185, v179
	v_cndmask_b32_e64 v130, 0, v184, s[6:7]
	s_or_b64 s[4:5], vcc, s[4:5]
	v_add_f32_e32 v179, v183, v179
	v_cndmask_b32_e64 v184, v130, 0, s[4:5]
	v_add_f32_e32 v179, v184, v179
	v_cvt_pk_bf16_f32 v130, v131, v185
	v_cvt_pk_bf16_f32 v131, v183, v184
	s_mov_b64 s[4:5], 0

; #define LAS __attribute__((address_space(3)))
; __device__ __forceinline__ v4i16_t vtr(const LAS unsigned char* p) { return __builtin_amdgcn_ds_read_tr16_b64_v4i16((LAS v4i16_t*)p); }
; #define MFMA16(a, b, c) __builtin_amdgcn_mfma_f32_16x16x32_bf16((a), (b), (c), 0, 0, 0)
; template <int PASS>
; __device__ __forceinline__ void attn_pass(const Frame& F, const bf16_t* QKVA, bf16_t* OACC, float* LACC, bf16_t* Hout, float nb2) {
;     ...
;         if (PASS > 0) {
; #pragma unroll
;             for (int nt = 0; nt < 8; ++nt) { const u32x2 pv = *(const u32x2*)(op + 16 * nt); accO[nt] = (f32x4){bflo(pv.x), bfhi(pv.x), bflo(pv.y), bfhi(pv.y)}; }
;             lsum = (g == 0) ? LACC[tq * 8 + h] : 0.f;
;     ...
;             const bf16x8 pa = __builtin_bit_cast(bf16x8, pw);
;             const int kt0 = w + 2 * ks, kt1 = (kt0 + 1 < 16) ? kt0 + 1 : 15;
;             const LAS unsigned char* v0 = Vl + (16 * kt0 + 4 * g + q4) * VST + 8 * p4;
;             const LAS unsigned char* v1 = Vl + (16 * kt1 + 4 * g + q4) * VST + 8 * p4;
; #pragma unroll
;             for (int nt = 0; nt < 8; ++nt) {
;                 const v4i16_t lo = vtr(v0 + 32 * nt), hi = vtr(v1 + 32 * nt);
;                 const bf16x8 vf = __builtin_shufflevector(lo, hi, 0, 1, 2, 3, 4, 5, 6, 7);
;                 accO[nt] = MFMA16(vf, pa, accO[nt]);
;             }
.LBB0_550:
	s_or_b64 exec, exec, s[6:7]
	s_cmp_gt_i32 s9, 3
	s_waitcnt vmcnt(7)
	v_lshlrev_b32_e32 v124, 16, v110
	v_and_b32_e32 v125, 0xffff0000, v110
	v_lshlrev_b32_e32 v126, 16, v111
	v_and_b32_e32 v127, 0xffff0000, v111
	s_waitcnt vmcnt(6)
	v_lshlrev_b32_e32 v120, 16, v108
	v_and_b32_e32 v121, 0xffff0000, v108
	v_lshlrev_b32_e32 v122, 16, v109
	v_and_b32_e32 v123, 0xffff0000, v109
	s_waitcnt vmcnt(5)
	v_lshlrev_b32_e32 v116, 16, v106
	v_and_b32_e32 v117, 0xffff0000, v106
	v_lshlrev_b32_e32 v118, 16, v107
	v_and_b32_e32 v119, 0xffff0000, v107
	s_waitcnt vmcnt(4)
	v_lshlrev_b32_e32 v112, 16, v104
	v_and_b32_e32 v113, 0xffff0000, v104
	v_lshlrev_b32_e32 v114, 16, v105
	v_and_b32_e32 v115, 0xffff0000, v105
	s_waitcnt vmcnt(3)
	v_lshlrev_b32_e32 v108, 16, v102
	v_and_b32_e32 v109, 0xffff0000, v102
	v_lshlrev_b32_e32 v110, 16, v103
	v_and_b32_e32 v111, 0xffff0000, v103
	s_waitcnt vmcnt(2)
	v_lshlrev_b32_e32 v104, 16, v100
	v_and_b32_e32 v105, 0xffff0000, v100
	v_lshlrev_b32_e32 v106, 16, v101
	v_and_b32_e32 v107, 0xffff0000, v101
	s_waitcnt vmcnt(1)
	v_lshlrev_b32_e32 v100, 16, v96
	v_and_b32_e32 v101, 0xffff0000, v96
	v_lshlrev_b32_e32 v102, 16, v97
	v_and_b32_e32 v103, 0xffff0000, v97
	s_waitcnt vmcnt(0)
	v_lshlrev_b32_e32 v96, 16, v98
	v_and_b32_e32 v97, 0xffff0000, v98
	v_lshlrev_b32_e32 v98, 16, v99
	v_and_b32_e32 v99, 0xffff0000, v99
	s_cselect_b64 s[24:25], -1, 0
	s_mov_b32 s20, 0
	v_mov_b32_e32 v146, v171
	s_mov_b32 s42, s65
	s_min_i32 s98, s42, 15
	v_lshl_or_b32 v250, s98, 4, v135
	v_mad_u64_u32 v[252:253], s[98:99], v250, s28, v[150:151]
	ds_read_b128 v[214:217], v252
	ds_read_b128 v[218:221], v252 offset:64
	ds_read_b128 v[222:225], v252 offset:128
	ds_read_b128 v[226:229], v252 offset:192
	s_branch .LBB0_552
.LBB0_551:
	s_add_i32 s6, s42, 2
	s_min_i32 s6, s6, 15
	v_lshl_or_b32 v250, s6, 4, v135
	v_mad_u64_u32 v[252:253], s[6:7], v250, s28, v[150:151]
	ds_read_b128 v[214:217], v252
	ds_read_b128 v[218:221], v252 offset:64
	ds_read_b128 v[222:225], v252 offset:128
	ds_read_b128 v[226:229], v252 offset:192
	s_min_i32 s6, s42, 14
	v_add_u32_e32 v128, 0xffffff20, v146
	v_lshl_add_u32 v187, s6, 4, v166
	v_mad_u64_u32 v[198:199], s[6:7], v187, s29, v[152:153]
	ds_read_b64_tr_b16 v[188:189], v128
	ds_read_b64_tr_b16 v[190:191], v198
	v_cvt_pk_bf16_f32 v128, v129, v184
	v_cvt_pk_bf16_f32 v129, v185, v186
	v_add_u32_e32 v184, 0xffffff40, v146
	ds_read_b64_tr_b16 v[184:185], v184
	ds_read_b64_tr_b16 v[186:187], v198 offset:32
	ds_read_b64_tr_b16 v[192:193], v198 offset:64
	ds_read_b64_tr_b16 v[196:197], v198 offset:96
	s_waitcnt lgkmcnt(4)
	v_mfma_f32_16x16x32_bf16 v[124:127], v[188:191], v[128:131], v[124:127]
	v_add_u32_e32 v188, 0xffffff60, v146
	ds_read_b64_tr_b16 v[190:191], v188
	v_add_u32_e32 v188, 0xffffff80, v146
	v_add_u32_e32 v189, 0xffffffa0, v146
	ds_read_b64_tr_b16 v[194:195], v188
	ds_read_b64_tr_b16 v[188:189], v189
	s_waitcnt lgkmcnt(5)
	v_mfma_f32_16x16x32_bf16 v[120:123], v[184:187], v[128:131], v[120:123]
	v_subrev_u32_e32 v184, 64, v146
	s_add_i32 s20, s20, 32
	s_add_i32 s42, s42, 2
	s_waitcnt lgkmcnt(2)
	v_mfma_f32_16x16x32_bf16 v[116:119], v[190:193], v[128:131], v[116:119]
	ds_read_b64_tr_b16 v[190:191], v198 offset:128
	s_cmpk_eq_i32 s20, 0xa0
	s_waitcnt lgkmcnt(2)
	v_mfma_f32_16x16x32_bf16 v[112:115], v[194:197], v[128:131], v[112:115]
	ds_read_b64_tr_b16 v[184:185], v184
	ds_read_b64_tr_b16 v[186:187], v198 offset:160
	ds_read_b64_tr_b16 v[192:193], v198 offset:192
	ds_read_b64_tr_b16 v[196:197], v198 offset:224
	s_waitcnt lgkmcnt(4)
	v_mfma_f32_16x16x32_bf16 v[108:111], v[188:191], v[128:131], v[108:111]
	v_subrev_u32_e32 v188, 32, v146
	ds_read_b64_tr_b16 v[190:191], v188
	ds_read_b64_tr_b16 v[194:195], v146
	v_add_u32_e32 v146, 0x2400, v146
	s_waitcnt lgkmcnt(4)
	v_mfma_f32_16x16x32_bf16 v[104:107], v[184:187], v[128:131], v[104:107]
	s_waitcnt lgkmcnt(1)
	v_mfma_f32_16x16x32_bf16 v[100:103], v[190:193], v[128:131], v[100:103]
	s_waitcnt lgkmcnt(0)
	v_mfma_f32_16x16x32_bf16 v[96:99], v[194:197], v[128:131], v[96:99]
	s_cbranch_scc1 .LBB0_556
; #define LAS __attribute__((address_space(3)))
; __device__ __forceinline__ unsigned cvtpk_s(float lo, float hi) { f32x2_t v = {lo, hi}; bf16x2_t b = __builtin_convertvector(v, bf16x2_t); return __builtin_bit_cast(unsigned, b); }
; #define MFMA16(a, b, c) __builtin_amdgcn_mfma_f32_16x16x32_bf16((a), (b), (c), 0, 0, 0)
; template <int PASS>
; __device__ __forceinline__ void attn_pass(const Frame& F, const bf16_t* QKVA, bf16_t* OACC, float* LACC, bf16_t* Hout, float nb2) {
;     ...
;         for (int ks = 0; ks < 5; ++ks) {
;             u32x4 pw;
; #pragma unroll
;             for (int half = 0; half < 2; ++half) {
;                 const int kt = w + 2 * ks + half; const int ktc = kt < 16 ? kt : 15;
;                 if (ks == 4 && half == 1) { pw.z = 0u; pw.w = 0u; continue; }
;                 f32x4 sv = (f32x4){0.f, 0.f, 0.f, 0.f};
; #pragma unroll
;                 for (int kk = 0; kk < 4; ++kk) { const bf16x8 a = *(const LAS bf16x8*)(Kl + (16 * ktc + c) * KST + (8 * g + 32 * kk) * 2); sv = MFMA16(a, qf[kk], sv); }
;                 float pj[4];
; #pragma unroll
;                 for (int j = 0; j < 4; ++j) { const int kj = 16 * kt + 4 * g + j; const bool valid = (kj >= qi) && (kj <= qi + 128) && (n > 0 || kj >= 128);
;                     pj[j] = valid ? __builtin_amdgcn_exp2f(sv[j] * SCL + nb2) : 0.f; lsum += pj[j]; }
;                 if (half == 0) { pw.x = cvtpk_s(pj[0], pj[1]); pw.y = cvtpk_s(pj[2], pj[3]); } else { pw.z = cvtpk_s(pj[0], pj[1]); pw.w = cvtpk_s(pj[2], pj[3]); }
;             }
.LBB0_552:
	s_add_i32 s6, s42, 1
	s_min_i32 s6, s6, 15
	v_lshl_or_b32 v246, s6, 4, v135
	v_mad_u64_u32 v[248:249], s[6:7], v246, s28, v[150:151]
	ds_read_b128 v[230:233], v248
	ds_read_b128 v[234:237], v248 offset:64
	ds_read_b128 v[238:241], v248 offset:128
	ds_read_b128 v[242:245], v248 offset:192
	s_waitcnt lgkmcnt(7)
	v_mfma_f32_16x16x32_bf16 v[184:187], v[214:217], v[16:19], 0
	v_add_u32_e32 v128, s20, v170
	v_add_u32_e32 v129, 1, v128
	v_cmp_lt_i32_e64 s[14:15], v129, v164
	s_waitcnt lgkmcnt(6)
	v_mfma_f32_16x16x32_bf16 v[184:187], v[218:221], v[12:15], v[184:187]
	v_cmp_lt_i32_e32 vcc, v128, v164
	v_cmp_gt_i32_e64 s[6:7], v128, v165
	v_add_u32_e32 v130, 2, v128
	s_waitcnt lgkmcnt(5)
	v_mfma_f32_16x16x32_bf16 v[184:187], v[222:225], v[8:11], v[184:187]
	v_cmp_lt_i32_e64 s[8:9], s38, v128
	v_cmp_lt_i32_e64 s[12:13], s39, v128
	s_or_b64 s[34:35], vcc, s[6:7]
	s_waitcnt lgkmcnt(4)
	v_mfma_f32_16x16x32_bf16 v[184:187], v[226:229], v[4:7], v[184:187]
	v_cmp_lt_i32_e64 s[6:7], s38, v130
	s_or_b64 s[8:9], s[24:25], s[8:9]
	s_or_b64 vcc, s[24:25], s[12:13]
	s_or_b64 s[6:7], s[24:25], s[6:7]
	v_cmp_ge_i32_e64 s[10:11], v128, v165
	s_nop 2
	v_fmamk_f32 v129, v184, 0x3e0293ee, v208
	v_fmamk_f32 v131, v185, 0x3e0293ee, v208
	v_fmamk_f32 v184, v186, 0x3e0293ee, v208
	v_exp_f32_e32 v129, v129
	v_exp_f32_e32 v131, v131
	v_exp_f32_e32 v184, v184
	v_fmamk_f32 v185, v187, 0x3e0293ee, v208
	v_exp_f32_e32 v185, v185
	v_cmp_lt_i32_e64 s[16:17], v130, v164
	v_cndmask_b32_e64 v129, 0, v129, s[8:9]
	v_cndmask_b32_e32 v131, 0, v131, vcc
	v_cmp_gt_i32_e32 vcc, v130, v165
	v_cndmask_b32_e64 v130, 0, v184, s[6:7]
	v_add_u32_e32 v184, 3, v128
	s_or_b64 s[10:11], s[14:15], s[10:11]
	v_cmp_lt_i32_e64 s[8:9], s38, v184
	v_cndmask_b32_e64 v129, v129, 0, s[34:35]
	s_or_b64 s[12:13], s[16:17], vcc
	v_cmp_lt_i32_e32 vcc, v184, v164
	v_cmp_gt_i32_e64 s[6:7], v184, v165
	s_or_b64 s[8:9], s[24:25], s[8:9]
	v_add_f32_e32 v155, v155, v129
	v_cndmask_b32_e64 v184, v131, 0, s[10:11]
	v_cndmask_b32_e64 v186, 0, v185, s[8:9]
	s_or_b64 s[6:7], vcc, s[6:7]
	v_add_f32_e32 v131, v184, v155
	v_cndmask_b32_e64 v185, v130, 0, s[12:13]
	v_add_f32_e32 v130, v185, v131
	v_cndmask_b32_e64 v186, v186, 0, s[6:7]
	s_cmpk_lg_i32 s20, 0x80
	v_add_f32_e32 v187, v186, v130
	s_mov_b64 s[6:7], -1
	s_cbranch_scc0 .LBB0_554
	s_waitcnt lgkmcnt(3)
	v_mfma_f32_16x16x32_bf16 v[188:191], v[230:233], v[16:19], 0
	v_add_u32_e32 v131, 16, v128
	v_cmp_lt_i32_e32 vcc, v131, v164
	v_cmp_gt_i32_e64 s[6:7], v131, v165
	s_waitcnt lgkmcnt(2)
	v_mfma_f32_16x16x32_bf16 v[188:191], v[234:237], v[12:15], v[188:191]
	v_cmp_lt_i32_e64 s[8:9], s38, v131
	v_cmp_ge_i32_e64 s[12:13], v131, v165
	v_cmp_lt_i32_e64 s[14:15], s39, v131
	s_waitcnt lgkmcnt(1)
	v_mfma_f32_16x16x32_bf16 v[188:191], v[238:241], v[8:11], v[188:191]
	v_add_u32_e32 v155, 17, v128
	v_cmp_lt_i32_e64 s[10:11], v155, v164
	s_or_b64 s[8:9], s[24:25], s[8:9]
	s_waitcnt lgkmcnt(0)
	v_mfma_f32_16x16x32_bf16 v[188:191], v[242:245], v[4:7], v[188:191]
	s_or_b64 s[6:7], vcc, s[6:7]
	v_add_u32_e32 v209, 18, v128
	v_cmp_lt_i32_e64 s[16:17], v209, v164
	v_cmp_gt_i32_e32 vcc, v209, v165
	v_add_u32_e32 v128, 19, v128
	s_nop 2
	v_fmamk_f32 v130, v188, 0x3e0293ee, v208
	v_fmamk_f32 v131, v189, 0x3e0293ee, v208
	v_exp_f32_e32 v130, v130
	v_exp_f32_e32 v131, v131
	v_fmamk_f32 v155, v190, 0x3e0293ee, v208
	v_exp_f32_e32 v155, v155
	v_cndmask_b32_e64 v130, 0, v130, s[8:9]
	s_or_b64 s[8:9], s[24:25], s[14:15]
	v_cndmask_b32_e64 v131, 0, v131, s[8:9]
	v_cndmask_b32_e64 v130, v130, 0, s[6:7]
	s_or_b64 s[6:7], s[10:11], s[12:13]
	v_cndmask_b32_e64 v131, v131, 0, s[6:7]
	v_cmp_lt_i32_e64 s[6:7], s38, v209
	s_or_b64 s[6:7], s[24:25], s[6:7]
	v_add_f32_e32 v188, v187, v130
	v_cndmask_b32_e64 v155, 0, v155, s[6:7]
	s_or_b64 s[6:7], s[16:17], vcc
	v_add_f32_e32 v188, v131, v188
	v_cndmask_b32_e64 v189, v155, 0, s[6:7]
	v_add_f32_e32 v155, v189, v188
	v_fmamk_f32 v188, v191, 0x3e0293ee, v208
	v_exp_f32_e32 v188, v188
	v_cmp_lt_i32_e64 s[8:9], s38, v128
	v_cmp_lt_i32_e32 vcc, v128, v164
	v_cmp_gt_i32_e64 s[6:7], v128, v165
	s_or_b64 s[8:9], s[24:25], s[8:9]
	v_cndmask_b32_e64 v128, 0, v188, s[8:9]
	s_or_b64 s[6:7], vcc, s[6:7]
	v_cndmask_b32_e64 v128, v128, 0, s[6:7]
	v_add_f32_e32 v155, v128, v155
	v_cvt_pk_bf16_f32 v130, v130, v131
	v_cvt_pk_bf16_f32 v131, v189, v128
	s_mov_b64 s[6:7], 0

; #define LAS __attribute__((address_space(3)))
; __device__ __forceinline__ v4i16_t vtr(const LAS unsigned char* p) { return __builtin_amdgcn_ds_read_tr16_b64_v4i16((LAS v4i16_t*)p); }
; #define MFMA16(a, b, c) __builtin_amdgcn_mfma_f32_16x16x32_bf16((a), (b), (c), 0, 0, 0)
; template <int PASS>
; __device__ __forceinline__ void attn_pass(const Frame& F, const bf16_t* QKVA, bf16_t* OACC, float* LACC, bf16_t* Hout, float nb2) {
;     ...
;         if (PASS > 0) {
; #pragma unroll
;             for (int nt = 0; nt < 8; ++nt) { const u32x2 pv = *(const u32x2*)(op + 16 * nt); accO[nt] = (f32x4){bflo(pv.x), bfhi(pv.x), bflo(pv.y), bfhi(pv.y)}; }
;             lsum = (g == 0) ? LACC[tq * 8 + h] : 0.f;
;     ...
;             const bf16x8 pa = __builtin_bit_cast(bf16x8, pw);
;             const int kt0 = w + 2 * ks, kt1 = (kt0 + 1 < 16) ? kt0 + 1 : 15;
;             const LAS unsigned char* v0 = Vl + (16 * kt0 + 4 * g + q4) * VST + 8 * p4;
;             const LAS unsigned char* v1 = Vl + (16 * kt1 + 4 * g + q4) * VST + 8 * p4;
; #pragma unroll
;             for (int nt = 0; nt < 8; ++nt) {
;                 const v4i16_t lo = vtr(v0 + 32 * nt), hi = vtr(v1 + 32 * nt);
;                 const bf16x8 vf = __builtin_shufflevector(lo, hi, 0, 1, 2, 3, 4, 5, 6, 7);
;                 accO[nt] = MFMA16(vf, pa, accO[nt]);
;             }
.LBB0_632:
	s_or_b64 exec, exec, s[4:5]
	s_lshl_b32 s16, s6, 7
	s_cmp_gt_i32 s7, 15
	s_waitcnt vmcnt(7)
	v_lshlrev_b32_e32 v124, 16, v110
	v_and_b32_e32 v125, 0xffff0000, v110
	v_lshlrev_b32_e32 v126, 16, v111
	v_and_b32_e32 v127, 0xffff0000, v111
	s_waitcnt vmcnt(6)
	v_lshlrev_b32_e32 v120, 16, v108
	v_and_b32_e32 v121, 0xffff0000, v108
	v_lshlrev_b32_e32 v122, 16, v109
	v_and_b32_e32 v123, 0xffff0000, v109
	s_waitcnt vmcnt(5)
	v_lshlrev_b32_e32 v116, 16, v106
	v_and_b32_e32 v117, 0xffff0000, v106
	v_lshlrev_b32_e32 v118, 16, v107
	v_and_b32_e32 v119, 0xffff0000, v107
	s_waitcnt vmcnt(4)
	v_lshlrev_b32_e32 v112, 16, v104
	v_and_b32_e32 v113, 0xffff0000, v104
	v_lshlrev_b32_e32 v114, 16, v105
	v_and_b32_e32 v115, 0xffff0000, v105
	s_waitcnt vmcnt(3)
	v_lshlrev_b32_e32 v108, 16, v102
	v_and_b32_e32 v109, 0xffff0000, v102
	v_lshlrev_b32_e32 v110, 16, v103
	v_and_b32_e32 v111, 0xffff0000, v103
	s_waitcnt vmcnt(2)
	v_lshlrev_b32_e32 v104, 16, v100
	v_and_b32_e32 v105, 0xffff0000, v100
	v_lshlrev_b32_e32 v106, 16, v101
	v_and_b32_e32 v107, 0xffff0000, v101
	s_waitcnt vmcnt(1)
	v_lshlrev_b32_e32 v100, 16, v96
	v_and_b32_e32 v101, 0xffff0000, v96
	v_lshlrev_b32_e32 v102, 16, v97
	v_and_b32_e32 v103, 0xffff0000, v97
	s_waitcnt vmcnt(0)
	v_lshlrev_b32_e32 v96, 16, v98
	v_and_b32_e32 v97, 0xffff0000, v98
	v_lshlrev_b32_e32 v98, 16, v99
	v_and_b32_e32 v99, 0xffff0000, v99
	s_cselect_b64 s[20:21], -1, 0
	s_mov_b32 s29, 0
	v_mov_b32_e32 v135, v165
	s_mov_b32 s36, s65
	s_min_i32 s98, s36, 15
	v_lshl_or_b32 v250, s98, 4, v143
	v_mad_u64_u32 v[252:253], s[98:99], v250, s24, v[148:149]
	ds_read_b128 v[214:217], v252
	ds_read_b128 v[218:221], v252 offset:64
	ds_read_b128 v[222:225], v252 offset:128
	ds_read_b128 v[226:229], v252 offset:192
	s_branch .LBB0_634
.LBB0_633:
	s_add_i32 s4, s36, 2
	s_min_i32 s4, s4, 15
	v_lshl_or_b32 v250, s4, 4, v143
	v_mad_u64_u32 v[252:253], s[4:5], v250, s24, v[148:149]
	ds_read_b128 v[214:217], v252
	ds_read_b128 v[218:221], v252 offset:64
	ds_read_b128 v[222:225], v252 offset:128
	ds_read_b128 v[226:229], v252 offset:192
	s_min_i32 s4, s36, 14
	v_add_u32_e32 v128, 0xffffff20, v135
	v_lshl_add_u32 v181, s4, 4, v160
	v_mad_u64_u32 v[192:193], s[4:5], v181, s25, v[150:151]
	ds_read_b64_tr_b16 v[182:183], v128
	ds_read_b64_tr_b16 v[184:185], v192
	v_cvt_pk_bf16_f32 v128, v129, v178
	v_cvt_pk_bf16_f32 v129, v179, v180
	v_add_u32_e32 v178, 0xffffff40, v135
	ds_read_b64_tr_b16 v[178:179], v178
	ds_read_b64_tr_b16 v[180:181], v192 offset:32
	ds_read_b64_tr_b16 v[186:187], v192 offset:64
	ds_read_b64_tr_b16 v[190:191], v192 offset:96
	s_waitcnt lgkmcnt(4)
	v_mfma_f32_16x16x32_bf16 v[124:127], v[182:185], v[128:131], v[124:127]
	v_add_u32_e32 v182, 0xffffff60, v135
	ds_read_b64_tr_b16 v[184:185], v182
	v_add_u32_e32 v182, 0xffffff80, v135
	v_add_u32_e32 v183, 0xffffffa0, v135
	ds_read_b64_tr_b16 v[188:189], v182
	ds_read_b64_tr_b16 v[182:183], v183
	s_waitcnt lgkmcnt(5)
	v_mfma_f32_16x16x32_bf16 v[120:123], v[178:181], v[128:131], v[120:123]
	v_subrev_u32_e32 v178, 64, v135
	s_add_i32 s29, s29, 32
	s_add_i32 s36, s36, 2
	s_waitcnt lgkmcnt(2)
	v_mfma_f32_16x16x32_bf16 v[116:119], v[184:187], v[128:131], v[116:119]
	ds_read_b64_tr_b16 v[184:185], v192 offset:128
	s_cmpk_eq_i32 s29, 0xa0
	s_waitcnt lgkmcnt(2)
	v_mfma_f32_16x16x32_bf16 v[112:115], v[188:191], v[128:131], v[112:115]
	ds_read_b64_tr_b16 v[178:179], v178
	ds_read_b64_tr_b16 v[180:181], v192 offset:160
	ds_read_b64_tr_b16 v[186:187], v192 offset:192
	ds_read_b64_tr_b16 v[190:191], v192 offset:224
	s_waitcnt lgkmcnt(4)
	v_mfma_f32_16x16x32_bf16 v[108:111], v[182:185], v[128:131], v[108:111]
	v_subrev_u32_e32 v182, 32, v135
	ds_read_b64_tr_b16 v[184:185], v182
	ds_read_b64_tr_b16 v[188:189], v135
	v_add_u32_e32 v135, 0x2400, v135
	s_waitcnt lgkmcnt(4)
	v_mfma_f32_16x16x32_bf16 v[104:107], v[178:181], v[128:131], v[104:107]
	s_waitcnt lgkmcnt(1)
	v_mfma_f32_16x16x32_bf16 v[100:103], v[184:187], v[128:131], v[100:103]
	s_waitcnt lgkmcnt(0)
	v_mfma_f32_16x16x32_bf16 v[96:99], v[188:191], v[128:131], v[96:99]
	s_cbranch_scc1 .LBB0_627
; #define LAS __attribute__((address_space(3)))
; __device__ __forceinline__ unsigned cvtpk_s(float lo, float hi) { f32x2_t v = {lo, hi}; bf16x2_t b = __builtin_convertvector(v, bf16x2_t); return __builtin_bit_cast(unsigned, b); }
; #define MFMA16(a, b, c) __builtin_amdgcn_mfma_f32_16x16x32_bf16((a), (b), (c), 0, 0, 0)
; template <int PASS>
; __device__ __forceinline__ void attn_pass(const Frame& F, const bf16_t* QKVA, bf16_t* OACC, float* LACC, bf16_t* Hout, float nb2) {
;     ...
;         for (int ks = 0; ks < 5; ++ks) {
;             u32x4 pw;
; #pragma unroll
;             for (int half = 0; half < 2; ++half) {
;                 const int kt = w + 2 * ks + half; const int ktc = kt < 16 ? kt : 15;
;                 if (ks == 4 && half == 1) { pw.z = 0u; pw.w = 0u; continue; }
;                 f32x4 sv = (f32x4){0.f, 0.f, 0.f, 0.f};
; #pragma unroll
;                 for (int kk = 0; kk < 4; ++kk) { const bf16x8 a = *(const LAS bf16x8*)(Kl + (16 * ktc + c) * KST + (8 * g + 32 * kk) * 2); sv = MFMA16(a, qf[kk], sv); }
;                 float pj[4];
; #pragma unroll
;                 for (int j = 0; j < 4; ++j) { const int kj = 16 * kt + 4 * g + j; const bool valid = (kj >= qi) && (kj <= qi + 128) && (n > 0 || kj >= 128);
;                     pj[j] = valid ? __builtin_amdgcn_exp2f(sv[j] * SCL + nb2) : 0.f; lsum += pj[j]; }
;                 if (half == 0) { pw.x = cvtpk_s(pj[0], pj[1]); pw.y = cvtpk_s(pj[2], pj[3]); } else { pw.z = cvtpk_s(pj[0], pj[1]); pw.w = cvtpk_s(pj[2], pj[3]); }
;             }
.LBB0_634:
	s_add_i32 s4, s36, 1
	s_min_i32 s4, s4, 15
	v_lshl_or_b32 v246, s4, 4, v143
	v_mad_u64_u32 v[248:249], s[4:5], v246, s24, v[148:149]
	ds_read_b128 v[230:233], v248
	ds_read_b128 v[234:237], v248 offset:64
	ds_read_b128 v[238:241], v248 offset:128
	ds_read_b128 v[242:245], v248 offset:192
	s_waitcnt lgkmcnt(7)
	v_mfma_f32_16x16x32_bf16 v[178:181], v[214:217], v[28:31], 0
	v_add_u32_e32 v128, s29, v164
	v_add_u32_e32 v129, 1, v128
	v_cmp_lt_i32_e64 s[12:13], v129, v158
	s_waitcnt lgkmcnt(6)
	v_mfma_f32_16x16x32_bf16 v[178:181], v[218:221], v[24:27], v[178:181]
	v_cmp_lt_i32_e32 vcc, v128, v158
	v_cmp_gt_i32_e64 s[4:5], v128, v159
	v_add_u32_e32 v130, 2, v128
	s_waitcnt lgkmcnt(5)
	v_mfma_f32_16x16x32_bf16 v[178:181], v[222:225], v[20:23], v[178:181]
	v_cmp_lt_i32_e64 s[6:7], s26, v128
	v_cmp_lt_i32_e64 s[10:11], s27, v128
	s_or_b64 s[34:35], vcc, s[4:5]
	s_waitcnt lgkmcnt(4)
	v_mfma_f32_16x16x32_bf16 v[178:181], v[226:229], v[16:19], v[178:181]
	v_cmp_lt_i32_e64 s[4:5], s26, v130
	s_or_b64 s[6:7], s[20:21], s[6:7]
	s_or_b64 vcc, s[20:21], s[10:11]
	s_or_b64 s[4:5], s[20:21], s[4:5]
	v_cmp_ge_i32_e64 s[8:9], v128, v159
	s_nop 2
	v_fmamk_f32 v129, v178, 0x3e0293ee, v208
	v_fmamk_f32 v131, v179, 0x3e0293ee, v208
	v_fmamk_f32 v178, v180, 0x3e0293ee, v208
	v_exp_f32_e32 v129, v129
	v_exp_f32_e32 v131, v131
	v_exp_f32_e32 v178, v178
	v_fmamk_f32 v179, v181, 0x3e0293ee, v208
	v_exp_f32_e32 v179, v179
	v_cmp_lt_i32_e64 s[14:15], v130, v158
	v_cndmask_b32_e64 v129, 0, v129, s[6:7]
	v_cndmask_b32_e32 v131, 0, v131, vcc
	v_cmp_gt_i32_e32 vcc, v130, v159
	v_cndmask_b32_e64 v130, 0, v178, s[4:5]
	v_add_u32_e32 v178, 3, v128
	s_or_b64 s[8:9], s[12:13], s[8:9]
	v_cmp_lt_i32_e64 s[6:7], s26, v178
	v_cndmask_b32_e64 v129, v129, 0, s[34:35]
	s_or_b64 s[10:11], s[14:15], vcc
	v_cmp_lt_i32_e32 vcc, v178, v158
	v_cmp_gt_i32_e64 s[4:5], v178, v159
	s_or_b64 s[6:7], s[20:21], s[6:7]
	v_add_f32_e32 v144, v144, v129
	v_cndmask_b32_e64 v178, v131, 0, s[8:9]
	v_cndmask_b32_e64 v180, 0, v179, s[6:7]
	s_or_b64 s[4:5], vcc, s[4:5]
	v_add_f32_e32 v131, v178, v144
	v_cndmask_b32_e64 v179, v130, 0, s[10:11]
	v_add_f32_e32 v130, v179, v131
	v_cndmask_b32_e64 v180, v180, 0, s[4:5]
	s_cmpk_lg_i32 s29, 0x80
	v_add_f32_e32 v181, v180, v130
	s_mov_b64 s[4:5], -1
	s_cbranch_scc0 .LBB0_636
	s_waitcnt lgkmcnt(3)
	v_mfma_f32_16x16x32_bf16 v[182:185], v[230:233], v[28:31], 0
	v_add_u32_e32 v131, 16, v128
	v_cmp_lt_i32_e32 vcc, v131, v158
	v_cmp_gt_i32_e64 s[4:5], v131, v159
	s_waitcnt lgkmcnt(2)
	v_mfma_f32_16x16x32_bf16 v[182:185], v[234:237], v[24:27], v[182:185]
	v_cmp_lt_i32_e64 s[6:7], s26, v131
	v_cmp_ge_i32_e64 s[10:11], v131, v159
	v_cmp_lt_i32_e64 s[12:13], s27, v131
	s_waitcnt lgkmcnt(1)
	v_mfma_f32_16x16x32_bf16 v[182:185], v[238:241], v[20:23], v[182:185]
	v_add_u32_e32 v144, 17, v128
	v_cmp_lt_i32_e64 s[8:9], v144, v158
	s_or_b64 s[6:7], s[20:21], s[6:7]
	s_waitcnt lgkmcnt(0)
	v_mfma_f32_16x16x32_bf16 v[182:185], v[242:245], v[16:19], v[182:185]
	s_or_b64 s[4:5], vcc, s[4:5]
	v_add_u32_e32 v198, 18, v128
	v_cmp_lt_i32_e64 s[14:15], v198, v158
	v_cmp_gt_i32_e32 vcc, v198, v159
	v_add_u32_e32 v128, 19, v128
	s_nop 2
	v_fmamk_f32 v130, v182, 0x3e0293ee, v208
	v_fmamk_f32 v131, v183, 0x3e0293ee, v208
	v_exp_f32_e32 v130, v130
	v_exp_f32_e32 v131, v131
	v_fmamk_f32 v144, v184, 0x3e0293ee, v208
	v_exp_f32_e32 v144, v144
	v_cndmask_b32_e64 v130, 0, v130, s[6:7]
	s_or_b64 s[6:7], s[20:21], s[12:13]
	v_cndmask_b32_e64 v131, 0, v131, s[6:7]
	v_cndmask_b32_e64 v130, v130, 0, s[4:5]
	s_or_b64 s[4:5], s[8:9], s[10:11]
	v_cndmask_b32_e64 v131, v131, 0, s[4:5]
	v_cmp_lt_i32_e64 s[4:5], s26, v198
	s_or_b64 s[4:5], s[20:21], s[4:5]
	v_add_f32_e32 v182, v181, v130
	v_cndmask_b32_e64 v144, 0, v144, s[4:5]
	s_or_b64 s[4:5], s[14:15], vcc
	v_add_f32_e32 v182, v131, v182
	v_cndmask_b32_e64 v183, v144, 0, s[4:5]
	v_add_f32_e32 v144, v183, v182
	v_fmamk_f32 v182, v185, 0x3e0293ee, v208
	v_exp_f32_e32 v182, v182
	v_cmp_lt_i32_e64 s[6:7], s26, v128
	v_cmp_lt_i32_e32 vcc, v128, v158
	v_cmp_gt_i32_e64 s[4:5], v128, v159
	s_or_b64 s[6:7], s[20:21], s[6:7]
	v_cndmask_b32_e64 v128, 0, v182, s[6:7]
	s_or_b64 s[4:5], vcc, s[4:5]
	v_cndmask_b32_e64 v128, v128, 0, s[4:5]
	v_add_f32_e32 v144, v128, v144
	v_cvt_pk_bf16_f32 v130, v130, v131
	v_cvt_pk_bf16_f32 v131, v183, v128
	s_mov_b64 s[4:5], 0

; __global__ void __launch_bounds__(NWAVES * 64, 2) fwd_megakernel(Args args) {
	.amdhsa_kernel _Z14fwd_megakernel4Args
		.amdhsa_group_segment_fixed_size 0
		.amdhsa_private_segment_fixed_size 0
		.amdhsa_kernarg_size 432
		.amdhsa_user_sgpr_count 2
		.amdhsa_user_sgpr_dispatch_ptr 0
		.amdhsa_user_sgpr_queue_ptr 0
		.amdhsa_user_sgpr_kernarg_segment_ptr 1
		.amdhsa_user_sgpr_dispatch_id 0
		.amdhsa_user_sgpr_kernarg_preload_length 0
		.amdhsa_user_sgpr_kernarg_preload_offset 0
		.amdhsa_user_sgpr_private_segment_size 0
		.amdhsa_uses_dynamic_stack 0
		.amdhsa_enable_private_segment 0
		.amdhsa_system_sgpr_workgroup_id_x 1
		.amdhsa_system_sgpr_workgroup_id_y 0
		.amdhsa_system_sgpr_workgroup_id_z 0
		.amdhsa_system_sgpr_workgroup_info 0
		.amdhsa_system_vgpr_workitem_id 2
		.amdhsa_next_free_vgpr 255
		.amdhsa_next_free_sgpr 100
		.amdhsa_accum_offset 256
		.amdhsa_reserve_vcc 1
		.amdhsa_float_round_mode_32 0
		.amdhsa_float_round_mode_16_64 0
		.amdhsa_float_denorm_mode_32 3
		.amdhsa_float_denorm_mode_16_64 3
		.amdhsa_dx10_clamp 1
		.amdhsa_ieee_mode 1
		.amdhsa_fp16_overflow 0
		.amdhsa_tg_split 0
		.amdhsa_exception_fp_ieee_invalid_op 0
		.amdhsa_exception_fp_denorm_src 0
		.amdhsa_exception_fp_ieee_div_zero 0
		.amdhsa_exception_fp_ieee_overflow 0
		.amdhsa_exception_fp_ieee_underflow 0
		.amdhsa_exception_fp_ieee_inexact 0
		.amdhsa_exception_int_div_zero 0
	.end_amdhsa_kernel

; __global__ void __launch_bounds__(NWAVES * 64, 2) fwd_megakernel(Args args) {
amdhsa.kernels:
  - .agpr_count:     0
    .args:
      - .offset:         0
        .size:           176
        .value_kind:     by_value
      - .offset:         176
        .size:           4
        .value_kind:     hidden_block_count_x
      - .offset:         180
        .size:           4
        .value_kind:     hidden_block_count_y
      - .offset:         184
        .size:           4
        .value_kind:     hidden_block_count_z
      - .offset:         188
        .size:           2
        .value_kind:     hidden_group_size_x
      - .offset:         190
        .size:           2
        .value_kind:     hidden_group_size_y
      - .offset:         192
        .size:           2
        .value_kind:     hidden_group_size_z
      - .offset:         194
        .size:           2
        .value_kind:     hidden_remainder_x
      - .offset:         196
        .size:           2
        .value_kind:     hidden_remainder_y
      - .offset:         198
        .size:           2
        .value_kind:     hidden_remainder_z
      - .offset:         216
        .size:           8
        .value_kind:     hidden_global_offset_x
      - .offset:         224
        .size:           8
        .value_kind:     hidden_global_offset_y
      - .offset:         232
        .size:           8
        .value_kind:     hidden_global_offset_z
      - .offset:         240
        .size:           2
        .value_kind:     hidden_grid_dims
      - .offset:         264
        .size:           8
        .value_kind:     hidden_multigrid_sync_arg
      - .offset:         296
        .size:           4
        .value_kind:     hidden_dynamic_lds_size
    .group_segment_fixed_size: 0
    .kernarg_segment_align: 8
    .kernarg_segment_size: 432
    .language:       OpenCL C
    .language_version:
      - 2
      - 0
    .max_flat_workgroup_size: 512
    .name:           _Z14fwd_megakernel4Args
    .private_segment_fixed_size: 0
    .sgpr_count:     106
    .sgpr_spill_count: 22
    .symbol:         _Z14fwd_megakernel4Args.kd
    .uniform_work_group_size: 1
    .uses_dynamic_stack: false
    .vgpr_count:     255
    .vgpr_spill_count: 0
    .wavefront_size: 64
